# pre-norm: per-token pipeline (a token is normalised and stored as soon as its row has arrived, instead of after all six)
# speedup vs baseline: 1.0071x; 1.0061x over previous
.LBB0_179:
	v_readlane_b32 s4, v255, 62
	s_nop 3
	s_cmp_eq_u32 s4, 2
	s_cbranch_scc1 .LBB0_193
	v_readlane_b32 s4, v253, 2
	v_readlane_b32 s5, v253, 3
	s_andn2_b64 vcc, exec, s[4:5]
	s_cbranch_vccnz .Lp1_after_norm
	v_mov_b32_e32 v0, v195
	s_mul_i32 s4, s2, s89
	s_nop 0
	v_add_u32_e32 v1, s4, v0
	s_nop 0
	v_readfirstlane_b32 s4, v1
	s_cmp_gt_u32 s4, 0xbffff
	s_cbranch_scc1 .Lp1_after_norm
	v_mbcnt_lo_u32_b32 v1, -1, 0
	v_mbcnt_hi_u32_b32 v1, -1, v1
	v_and_b32_e32 v2, 64, v1
	v_add_u32_e32 v2, 64, v2
	v_xor_b32_e32 v3, 32, v1
	v_cmp_lt_i32_e32 vcc, v3, v2
	s_lshr_b32 s17, s66, 6
	s_waitcnt lgkmcnt(0)
	s_add_u32 s39, s6, 0x1e0000
	v_cndmask_b32_e32 v3, v1, v3, vcc
	v_lshlrev_b32_e32 v103, 2, v3
	v_xor_b32_e32 v3, 16, v1
	v_cmp_lt_i32_e32 vcc, v3, v2
	s_addc_u32 s40, s7, 0
	s_lshr_b32 s41, s4, 6
	v_cndmask_b32_e32 v3, v1, v3, vcc
	v_lshlrev_b32_e32 v108, 2, v3
	v_xor_b32_e32 v3, 8, v1
	v_cmp_lt_i32_e32 vcc, v3, v2
	s_load_dwordx2 s[4:5], s[8:9], 0x30
	v_lshlrev_b32_e32 v0, 2, v0
	v_cndmask_b32_e32 v3, v1, v3, vcc
	v_lshlrev_b32_e32 v109, 2, v3
	v_xor_b32_e32 v3, 4, v1
	v_cmp_lt_i32_e32 vcc, v3, v2
	v_and_b32_e32 v0, 0xfc, v0
	v_mov_b32_e32 v97, 0
	v_cndmask_b32_e32 v3, v1, v3, vcc
	v_lshlrev_b32_e32 v110, 2, v3
	v_xor_b32_e32 v3, 2, v1
	v_cmp_lt_i32_e32 vcc, v3, v2
	v_lshlrev_b32_e32 v96, 2, v0
	s_waitcnt lgkmcnt(0)
	v_lshl_add_u64 v[98:99], s[4:5], 0, v[96:97]
	v_cndmask_b32_e32 v3, v1, v3, vcc
	v_lshlrev_b32_e32 v111, 2, v3
	v_xor_b32_e32 v3, 1, v1
	v_cmp_lt_i32_e32 vcc, v3, v2
	v_lshlrev_b32_e32 v96, 1, v0
	v_or_b32_e32 v2, 0x100, v0
	v_cndmask_b32_e32 v1, v1, v3, vcc
	v_or_b32_e32 v4, 0x200, v0
	v_or_b32_e32 v6, 0x300, v0
	v_lshl_add_u64 v[8:9], s[6:7], 0, v[96:97]
	s_mov_b64 s[4:5], 0x39fe000
	s_mul_i32 s38, s17, 6
	s_mov_b32 s13, 0
	v_lshlrev_b32_e32 v112, 2, v1
	v_lshl_add_u64 v[100:101], v[8:9], 0, s[4:5]
	s_lshl_b32 s14, s41, 10
	s_mul_i32 s42, s17, 0x1800
	s_lshl_b32 s43, s17, 1
	s_lshl_b32 s44, s17, 11
	s_mul_i32 s45, s17, 3
	s_mul_i32 s46, s17, 0xc00
	s_lshl_b32 s47, s17, 2
	s_lshl_b32 s48, s17, 12
	s_mul_i32 s49, s17, 5
	s_mul_i32 s50, s17, 0x1400
	s_lshl_b32 s51, s17, 10
	v_mov_b32_e32 v113, 0x1000
	v_lshlrev_b32_e32 v114, 2, v0
	s_mov_b32 s16, 0x3a800000
	v_mov_b32_e32 v102, 0x358637bd
	s_mov_b32 s52, 0x800000
	v_lshlrev_b32_e32 v115, 2, v2
	v_lshlrev_b32_e32 v116, 2, v4
	v_lshlrev_b32_e32 v117, 2, v6
	s_load_dwordx2 s[18:19], s[8:9], 0x0
	s_load_dwordx2 s[20:21], s[8:9], 0x8
	s_lshl_b32 s12, s41, 12
	s_lshl_b32 s15, s41, 11
	s_add_u32 s46, s6, 0x39fe000
	s_addc_u32 s47, s7, 0
	s_add_u32 s46, s46, s15
	s_addc_u32 s47, s47, 0
	global_load_dwordx4 v[144:147], v[98:99], off
	global_load_dwordx4 v[148:151], v[98:99], off offset:1024
	global_load_dwordx4 v[152:155], v[98:99], off offset:2048
	global_load_dwordx4 v[156:159], v[98:99], off offset:3072
	s_waitcnt lgkmcnt(0)
	s_add_u32 s24, s18, s12
	s_addc_u32 s25, s19, 0
	s_add_u32 s26, s24, 0x800000
	s_addc_u32 s27, s25, 0
	s_add_u32 s28, s20, s12
	s_addc_u32 s29, s21, 0
	s_add_u32 s30, s28, 0x800000
	s_addc_u32 s31, s29, 0
	s_add_u32 s34, s30, 0x800000
	s_addc_u32 s35, s31, 0
	s_add_u32 s36, s34, 0x800000
	s_addc_u32 s37, s35, 0
	global_load_dwordx4 v[0:3], v114, s[24:25] nt
	global_load_dwordx4 v[4:7], v114, s[24:25] offset:1024 nt
	global_load_dwordx4 v[8:11], v114, s[24:25] offset:2048 nt
	global_load_dwordx4 v[12:15], v114, s[24:25] offset:3072 nt
	global_load_dwordx4 v[16:19], v114, s[26:27] nt
	global_load_dwordx4 v[20:23], v114, s[26:27] offset:1024 nt
	global_load_dwordx4 v[24:27], v114, s[26:27] offset:2048 nt
	global_load_dwordx4 v[28:31], v114, s[26:27] offset:3072 nt
	global_load_dwordx4 v[32:35], v114, s[28:29] nt
	global_load_dwordx4 v[36:39], v114, s[28:29] offset:1024 nt
	global_load_dwordx4 v[40:43], v114, s[28:29] offset:2048 nt
	global_load_dwordx4 v[44:47], v114, s[28:29] offset:3072 nt
	global_load_dwordx4 v[48:51], v114, s[30:31] nt
	global_load_dwordx4 v[52:55], v114, s[30:31] offset:1024 nt
	global_load_dwordx4 v[56:59], v114, s[30:31] offset:2048 nt
	global_load_dwordx4 v[60:63], v114, s[30:31] offset:3072 nt
	global_load_dwordx4 v[64:67], v114, s[34:35] nt
	global_load_dwordx4 v[68:71], v114, s[34:35] offset:1024 nt
	global_load_dwordx4 v[72:75], v114, s[34:35] offset:2048 nt
	global_load_dwordx4 v[76:79], v114, s[34:35] offset:3072 nt
	global_load_dwordx4 v[80:83], v114, s[36:37] nt
	global_load_dwordx4 v[84:87], v114, s[36:37] offset:1024 nt
	global_load_dwordx4 v[88:91], v114, s[36:37] offset:2048 nt
	global_load_dwordx4 v[92:95], v114, s[36:37] offset:3072 nt
	s_add_u32 s48, s39, 0x0
	s_addc_u32 s49, s40, 0
	s_add_u32 s50, s48, 0x1000
	s_addc_u32 s51, s49, 0
	global_load_dwordx4 v[160:163], v114, s[50:51]
	global_load_dwordx4 v[164:167], v114, s[50:51] offset:1024
	global_load_dwordx4 v[168:171], v114, s[50:51] offset:2048
	global_load_dwordx4 v[172:175], v114, s[50:51] offset:3072
	global_load_dwordx4 v[176:179], v114, s[48:49]
	global_load_dwordx4 v[180:183], v114, s[48:49] offset:1024
	global_load_dwordx4 v[184:187], v114, s[48:49] offset:2048
	global_load_dwordx4 v[188:191], v114, s[48:49] offset:3072
	s_add_u32 s48, s39, 0x3000
	s_addc_u32 s49, s40, 0
	s_add_u32 s50, s48, 0x1000
	s_addc_u32 s51, s49, 0
	global_load_dwordx4 v[196:199], v114, s[50:51]
	global_load_dwordx4 v[200:203], v114, s[50:51] offset:1024
	global_load_dwordx4 v[204:207], v114, s[50:51] offset:2048
	global_load_dwordx4 v[208:211], v114, s[50:51] offset:3072
	global_load_dwordx4 v[212:215], v114, s[48:49]
	global_load_dwordx4 v[216:219], v114, s[48:49] offset:1024
	global_load_dwordx4 v[220:223], v114, s[48:49] offset:2048
	global_load_dwordx4 v[224:227], v114, s[48:49] offset:3072
	s_add_u32 s48, s39, 0x6000
	s_addc_u32 s49, s40, 0
	s_add_u32 s50, s48, 0x1000
	s_addc_u32 s51, s49, 0
	global_load_dwordx4 v[228:231], v114, s[50:51]
	global_load_dwordx4 v[232:235], v114, s[50:51] offset:1024
	global_load_dwordx4 v[236:239], v114, s[50:51] offset:2048
	global_load_dwordx4 v[240:243], v114, s[50:51] offset:3072
	global_load_dwordx4 v[244:247], v114, s[48:49]
	global_load_dwordx4 v[248:251], v114, s[48:49] offset:1024
	global_load_dwordx4 v[118:121], v114, s[48:49] offset:2048
	global_load_dwordx4 v[122:125], v114, s[48:49] offset:3072
	s_waitcnt vmcnt(48)
	s_waitcnt vmcnt(47)
	v_mul_f32_e32 v132, v1, v1
	v_fmac_f32_e32 v132, v0, v0
	v_fmac_f32_e32 v132, v2, v2
	v_fmac_f32_e32 v132, v3, v3
	s_waitcnt vmcnt(46)
	v_mul_f32_e32 v133, v5, v5
	v_fmac_f32_e32 v133, v4, v4
	v_fmac_f32_e32 v133, v6, v6
	v_fmac_f32_e32 v133, v7, v7
	s_waitcnt vmcnt(45)
	v_mul_f32_e32 v134, v9, v9
	v_fmac_f32_e32 v134, v8, v8
	v_fmac_f32_e32 v134, v10, v10
	v_fmac_f32_e32 v134, v11, v11
	s_waitcnt vmcnt(44)
	v_mul_f32_e32 v135, v13, v13
	v_fmac_f32_e32 v135, v12, v12
	v_fmac_f32_e32 v135, v14, v14
	v_fmac_f32_e32 v135, v15, v15
	v_add_f32_e32 v126, v132, v133
	v_add_f32_e32 v126, v126, v134
	v_add_f32_e32 v126, v126, v135
	ds_bpermute_b32 v136, v103, v126
	s_waitcnt lgkmcnt(0)
	v_add_f32_e32 v126, v126, v136
	ds_bpermute_b32 v136, v108, v126
	s_waitcnt lgkmcnt(0)
	v_add_f32_e32 v126, v126, v136
	ds_bpermute_b32 v136, v109, v126
	s_waitcnt lgkmcnt(0)
	v_add_f32_e32 v126, v126, v136
	ds_bpermute_b32 v136, v110, v126
	s_waitcnt lgkmcnt(0)
	v_add_f32_e32 v126, v126, v136
	ds_bpermute_b32 v136, v111, v126
	s_waitcnt lgkmcnt(0)
	v_add_f32_e32 v126, v126, v136
	ds_bpermute_b32 v136, v112, v126
	s_waitcnt lgkmcnt(0)
	v_add_f32_e32 v126, v126, v136
	v_fma_f32 v126, v126, s16, v102
	v_rsq_f32_e32 v126, v126
	s_nop 0
	s_waitcnt vmcnt(16)
	v_pk_add_f32 v[160:161], v[160:161], 1.0 op_sel_hi:[1,0]
	v_pk_add_f32 v[162:163], v[162:163], 1.0 op_sel_hi:[1,0]
	v_pk_add_f32 v[164:165], v[164:165], 1.0 op_sel_hi:[1,0]
	v_pk_add_f32 v[166:167], v[166:167], 1.0 op_sel_hi:[1,0]
	v_pk_add_f32 v[168:169], v[168:169], 1.0 op_sel_hi:[1,0]
	v_pk_add_f32 v[170:171], v[170:171], 1.0 op_sel_hi:[1,0]
	v_pk_add_f32 v[172:173], v[172:173], 1.0 op_sel_hi:[1,0]
	v_pk_add_f32 v[174:175], v[174:175], 1.0 op_sel_hi:[1,0]
	v_mul_f32_e32 v0, v0, v126
	v_mul_f32_e32 v1, v1, v126
	v_mul_f32_e32 v2, v2, v126
	v_mul_f32_e32 v3, v3, v126
	v_pk_mul_f32 v[0:1], v[0:1], v[144:145]
	v_pk_mul_f32 v[2:3], v[2:3], v[146:147]
	v_pk_fma_f32 v[0:1], v[0:1], v[160:161], v[176:177]
	v_pk_fma_f32 v[2:3], v[2:3], v[162:163], v[178:179]
	v_cvt_pk_bf16_f32 v0, v0, v1
	v_cvt_pk_bf16_f32 v1, v2, v3
	global_store_dwordx2 v96, v[0:1], s[46:47]
	v_mul_f32_e32 v4, v4, v126
	v_mul_f32_e32 v5, v5, v126
	v_mul_f32_e32 v6, v6, v126
	v_mul_f32_e32 v7, v7, v126
	v_pk_mul_f32 v[4:5], v[4:5], v[148:149]
	v_pk_mul_f32 v[6:7], v[6:7], v[150:151]
	v_pk_fma_f32 v[4:5], v[4:5], v[164:165], v[180:181]
	v_pk_fma_f32 v[6:7], v[6:7], v[166:167], v[182:183]
	v_cvt_pk_bf16_f32 v4, v4, v5
	v_cvt_pk_bf16_f32 v5, v6, v7
	global_store_dwordx2 v96, v[4:5], s[46:47] offset:512
	v_mul_f32_e32 v8, v8, v126
	v_mul_f32_e32 v9, v9, v126
	v_mul_f32_e32 v10, v10, v126
	v_mul_f32_e32 v11, v11, v126
	v_pk_mul_f32 v[8:9], v[8:9], v[152:153]
	v_pk_mul_f32 v[10:11], v[10:11], v[154:155]
	v_pk_fma_f32 v[8:9], v[8:9], v[168:169], v[184:185]
	v_pk_fma_f32 v[10:11], v[10:11], v[170:171], v[186:187]
	v_cvt_pk_bf16_f32 v8, v8, v9
	v_cvt_pk_bf16_f32 v9, v10, v11
	global_store_dwordx2 v96, v[8:9], s[46:47] offset:1024
	v_mul_f32_e32 v12, v12, v126
	v_mul_f32_e32 v13, v13, v126
	v_mul_f32_e32 v14, v14, v126
	v_mul_f32_e32 v15, v15, v126
	v_pk_mul_f32 v[12:13], v[12:13], v[156:157]
	v_pk_mul_f32 v[14:15], v[14:15], v[158:159]
	v_pk_fma_f32 v[12:13], v[12:13], v[172:173], v[188:189]
	v_pk_fma_f32 v[14:15], v[14:15], v[174:175], v[190:191]
	v_cvt_pk_bf16_f32 v12, v12, v13
	v_cvt_pk_bf16_f32 v13, v14, v15
	global_store_dwordx2 v96, v[12:13], s[46:47] offset:1536
	s_add_u32 s46, s46, 0x400000
	s_addc_u32 s47, s47, 0
	s_waitcnt vmcnt(47)
	v_mul_f32_e32 v132, v17, v17
	v_fmac_f32_e32 v132, v16, v16
	v_fmac_f32_e32 v132, v18, v18
	v_fmac_f32_e32 v132, v19, v19
	s_waitcnt vmcnt(46)
	v_mul_f32_e32 v133, v21, v21
	v_fmac_f32_e32 v133, v20, v20
	v_fmac_f32_e32 v133, v22, v22
	v_fmac_f32_e32 v133, v23, v23
	s_waitcnt vmcnt(45)
	v_mul_f32_e32 v134, v25, v25
	v_fmac_f32_e32 v134, v24, v24
	v_fmac_f32_e32 v134, v26, v26
	v_fmac_f32_e32 v134, v27, v27
	s_waitcnt vmcnt(44)
	v_mul_f32_e32 v135, v29, v29
	v_fmac_f32_e32 v135, v28, v28
	v_fmac_f32_e32 v135, v30, v30
	v_fmac_f32_e32 v135, v31, v31
	v_add_f32_e32 v127, v132, v133
	v_add_f32_e32 v127, v127, v134
	v_add_f32_e32 v127, v127, v135
	ds_bpermute_b32 v137, v103, v127
	s_waitcnt lgkmcnt(0)
	v_add_f32_e32 v127, v127, v137
	ds_bpermute_b32 v137, v108, v127
	s_waitcnt lgkmcnt(0)
	v_add_f32_e32 v127, v127, v137
	ds_bpermute_b32 v137, v109, v127
	s_waitcnt lgkmcnt(0)
	v_add_f32_e32 v127, v127, v137
	ds_bpermute_b32 v137, v110, v127
	s_waitcnt lgkmcnt(0)
	v_add_f32_e32 v127, v127, v137
	ds_bpermute_b32 v137, v111, v127
	s_waitcnt lgkmcnt(0)
	v_add_f32_e32 v127, v127, v137
	ds_bpermute_b32 v137, v112, v127
	s_waitcnt lgkmcnt(0)
	v_add_f32_e32 v127, v127, v137
	v_fma_f32 v127, v127, s16, v102
	v_rsq_f32_e32 v127, v127
	s_nop 0
	v_mul_f32_e32 v16, v16, v127
	v_mul_f32_e32 v17, v17, v127
	v_mul_f32_e32 v18, v18, v127
	v_mul_f32_e32 v19, v19, v127
	v_pk_mul_f32 v[16:17], v[16:17], v[144:145]
	v_pk_mul_f32 v[18:19], v[18:19], v[146:147]
	v_pk_fma_f32 v[16:17], v[16:17], v[160:161], v[176:177]
	v_pk_fma_f32 v[18:19], v[18:19], v[162:163], v[178:179]
	v_cvt_pk_bf16_f32 v16, v16, v17
	v_cvt_pk_bf16_f32 v17, v18, v19
	global_store_dwordx2 v96, v[16:17], s[46:47]
	v_mul_f32_e32 v20, v20, v127
	v_mul_f32_e32 v21, v21, v127
	v_mul_f32_e32 v22, v22, v127
	v_mul_f32_e32 v23, v23, v127
	v_pk_mul_f32 v[20:21], v[20:21], v[148:149]
	v_pk_mul_f32 v[22:23], v[22:23], v[150:151]
	v_pk_fma_f32 v[20:21], v[20:21], v[164:165], v[180:181]
	v_pk_fma_f32 v[22:23], v[22:23], v[166:167], v[182:183]
	v_cvt_pk_bf16_f32 v20, v20, v21
	v_cvt_pk_bf16_f32 v21, v22, v23
	global_store_dwordx2 v96, v[20:21], s[46:47] offset:512
	v_mul_f32_e32 v24, v24, v127
	v_mul_f32_e32 v25, v25, v127
	v_mul_f32_e32 v26, v26, v127
	v_mul_f32_e32 v27, v27, v127
	v_pk_mul_f32 v[24:25], v[24:25], v[152:153]
	v_pk_mul_f32 v[26:27], v[26:27], v[154:155]
	v_pk_fma_f32 v[24:25], v[24:25], v[168:169], v[184:185]
	v_pk_fma_f32 v[26:27], v[26:27], v[170:171], v[186:187]
	v_cvt_pk_bf16_f32 v24, v24, v25
	v_cvt_pk_bf16_f32 v25, v26, v27
	global_store_dwordx2 v96, v[24:25], s[46:47] offset:1024
	v_mul_f32_e32 v28, v28, v127
	v_mul_f32_e32 v29, v29, v127
	v_mul_f32_e32 v30, v30, v127
	v_mul_f32_e32 v31, v31, v127
	v_pk_mul_f32 v[28:29], v[28:29], v[156:157]
	v_pk_mul_f32 v[30:31], v[30:31], v[158:159]
	v_pk_fma_f32 v[28:29], v[28:29], v[172:173], v[188:189]
	v_pk_fma_f32 v[30:31], v[30:31], v[174:175], v[190:191]
	v_cvt_pk_bf16_f32 v28, v28, v29
	v_cvt_pk_bf16_f32 v29, v30, v31
	global_store_dwordx2 v96, v[28:29], s[46:47] offset:1536
	s_add_u32 s46, s46, 0x400000
	s_addc_u32 s47, s47, 0
	s_add_u32 s48, s39, 0x9000
	s_addc_u32 s49, s40, 0
	s_add_u32 s50, s48, 0x1000
	s_addc_u32 s51, s49, 0
	global_load_dwordx4 v[160:163], v114, s[50:51]
	global_load_dwordx4 v[164:167], v114, s[50:51] offset:1024
	global_load_dwordx4 v[168:171], v114, s[50:51] offset:2048
	global_load_dwordx4 v[172:175], v114, s[50:51] offset:3072
	global_load_dwordx4 v[176:179], v114, s[48:49]
	global_load_dwordx4 v[180:183], v114, s[48:49] offset:1024
	global_load_dwordx4 v[184:187], v114, s[48:49] offset:2048
	global_load_dwordx4 v[188:191], v114, s[48:49] offset:3072
	s_waitcnt vmcnt(55)
	v_mul_f32_e32 v132, v33, v33
	v_fmac_f32_e32 v132, v32, v32
	v_fmac_f32_e32 v132, v34, v34
	v_fmac_f32_e32 v132, v35, v35
	s_waitcnt vmcnt(54)
	v_mul_f32_e32 v133, v37, v37
	v_fmac_f32_e32 v133, v36, v36
	v_fmac_f32_e32 v133, v38, v38
	v_fmac_f32_e32 v133, v39, v39
	s_waitcnt vmcnt(53)
	v_mul_f32_e32 v134, v41, v41
	v_fmac_f32_e32 v134, v40, v40
	v_fmac_f32_e32 v134, v42, v42
	v_fmac_f32_e32 v134, v43, v43
	s_waitcnt vmcnt(52)
	v_mul_f32_e32 v135, v45, v45
	v_fmac_f32_e32 v135, v44, v44
	v_fmac_f32_e32 v135, v46, v46
	v_fmac_f32_e32 v135, v47, v47
	v_add_f32_e32 v128, v132, v133
	v_add_f32_e32 v128, v128, v134
	v_add_f32_e32 v128, v128, v135
	ds_bpermute_b32 v138, v103, v128
	s_waitcnt lgkmcnt(0)
	v_add_f32_e32 v128, v128, v138
	ds_bpermute_b32 v138, v108, v128
	s_waitcnt lgkmcnt(0)
	v_add_f32_e32 v128, v128, v138
	ds_bpermute_b32 v138, v109, v128
	s_waitcnt lgkmcnt(0)
	v_add_f32_e32 v128, v128, v138
	ds_bpermute_b32 v138, v110, v128
	s_waitcnt lgkmcnt(0)
	v_add_f32_e32 v128, v128, v138
	ds_bpermute_b32 v138, v111, v128
	s_waitcnt lgkmcnt(0)
	v_add_f32_e32 v128, v128, v138
	ds_bpermute_b32 v138, v112, v128
	s_waitcnt lgkmcnt(0)
	v_add_f32_e32 v128, v128, v138
	v_fma_f32 v128, v128, s16, v102
	v_rsq_f32_e32 v128, v128
	s_nop 0
	s_waitcnt vmcnt(24)
	v_pk_add_f32 v[196:197], v[196:197], 1.0 op_sel_hi:[1,0]
	v_pk_add_f32 v[198:199], v[198:199], 1.0 op_sel_hi:[1,0]
	v_pk_add_f32 v[200:201], v[200:201], 1.0 op_sel_hi:[1,0]
	v_pk_add_f32 v[202:203], v[202:203], 1.0 op_sel_hi:[1,0]
	v_pk_add_f32 v[204:205], v[204:205], 1.0 op_sel_hi:[1,0]
	v_pk_add_f32 v[206:207], v[206:207], 1.0 op_sel_hi:[1,0]
	v_pk_add_f32 v[208:209], v[208:209], 1.0 op_sel_hi:[1,0]
	v_pk_add_f32 v[210:211], v[210:211], 1.0 op_sel_hi:[1,0]
	v_mul_f32_e32 v32, v32, v128
	v_mul_f32_e32 v33, v33, v128
	v_mul_f32_e32 v34, v34, v128
	v_mul_f32_e32 v35, v35, v128
	v_pk_mul_f32 v[32:33], v[32:33], v[144:145]
	v_pk_mul_f32 v[34:35], v[34:35], v[146:147]
	v_pk_fma_f32 v[32:33], v[32:33], v[196:197], v[212:213]
	v_pk_fma_f32 v[34:35], v[34:35], v[198:199], v[214:215]
	v_cvt_pk_bf16_f32 v32, v32, v33
	v_cvt_pk_bf16_f32 v33, v34, v35
	global_store_dwordx2 v96, v[32:33], s[46:47]
	v_mul_f32_e32 v36, v36, v128
	v_mul_f32_e32 v37, v37, v128
	v_mul_f32_e32 v38, v38, v128
	v_mul_f32_e32 v39, v39, v128
	v_pk_mul_f32 v[36:37], v[36:37], v[148:149]
	v_pk_mul_f32 v[38:39], v[38:39], v[150:151]
	v_pk_fma_f32 v[36:37], v[36:37], v[200:201], v[216:217]
	v_pk_fma_f32 v[38:39], v[38:39], v[202:203], v[218:219]
	v_cvt_pk_bf16_f32 v36, v36, v37
	v_cvt_pk_bf16_f32 v37, v38, v39
	global_store_dwordx2 v96, v[36:37], s[46:47] offset:512
	v_mul_f32_e32 v40, v40, v128
	v_mul_f32_e32 v41, v41, v128
	v_mul_f32_e32 v42, v42, v128
	v_mul_f32_e32 v43, v43, v128
	v_pk_mul_f32 v[40:41], v[40:41], v[152:153]
	v_pk_mul_f32 v[42:43], v[42:43], v[154:155]
	v_pk_fma_f32 v[40:41], v[40:41], v[204:205], v[220:221]
	v_pk_fma_f32 v[42:43], v[42:43], v[206:207], v[222:223]
	v_cvt_pk_bf16_f32 v40, v40, v41
	v_cvt_pk_bf16_f32 v41, v42, v43
	global_store_dwordx2 v96, v[40:41], s[46:47] offset:1024
	v_mul_f32_e32 v44, v44, v128
	v_mul_f32_e32 v45, v45, v128
	v_mul_f32_e32 v46, v46, v128
	v_mul_f32_e32 v47, v47, v128
	v_pk_mul_f32 v[44:45], v[44:45], v[156:157]
	v_pk_mul_f32 v[46:47], v[46:47], v[158:159]
	v_pk_fma_f32 v[44:45], v[44:45], v[208:209], v[224:225]
	v_pk_fma_f32 v[46:47], v[46:47], v[210:211], v[226:227]
	v_cvt_pk_bf16_f32 v44, v44, v45
	v_cvt_pk_bf16_f32 v45, v46, v47
	global_store_dwordx2 v96, v[44:45], s[46:47] offset:1536
	s_add_u32 s46, s46, 0x400000
	s_addc_u32 s47, s47, 0
	s_add_u32 s48, s39, 0xc000
	s_addc_u32 s49, s40, 0
	s_add_u32 s50, s48, 0x1000
	s_addc_u32 s51, s49, 0
	global_load_dwordx4 v[196:199], v114, s[50:51]
	global_load_dwordx4 v[200:203], v114, s[50:51] offset:1024
	global_load_dwordx4 v[204:207], v114, s[50:51] offset:2048
	global_load_dwordx4 v[208:211], v114, s[50:51] offset:3072
	global_load_dwordx4 v[212:215], v114, s[48:49]
	global_load_dwordx4 v[216:219], v114, s[48:49] offset:1024
	global_load_dwordx4 v[220:223], v114, s[48:49] offset:2048
	global_load_dwordx4 v[224:227], v114, s[48:49] offset:3072
	s_waitcnt vmcnt(63)
	v_mul_f32_e32 v132, v49, v49
	v_fmac_f32_e32 v132, v48, v48
	v_fmac_f32_e32 v132, v50, v50
	v_fmac_f32_e32 v132, v51, v51
	s_waitcnt vmcnt(62)
	v_mul_f32_e32 v133, v53, v53
	v_fmac_f32_e32 v133, v52, v52
	v_fmac_f32_e32 v133, v54, v54
	v_fmac_f32_e32 v133, v55, v55
	s_waitcnt vmcnt(61)
	v_mul_f32_e32 v134, v57, v57
	v_fmac_f32_e32 v134, v56, v56
	v_fmac_f32_e32 v134, v58, v58
	v_fmac_f32_e32 v134, v59, v59
	s_waitcnt vmcnt(60)
	v_mul_f32_e32 v135, v61, v61
	v_fmac_f32_e32 v135, v60, v60
	v_fmac_f32_e32 v135, v62, v62
	v_fmac_f32_e32 v135, v63, v63
	v_add_f32_e32 v129, v132, v133
	v_add_f32_e32 v129, v129, v134
	v_add_f32_e32 v129, v129, v135
	ds_bpermute_b32 v139, v103, v129
	s_waitcnt lgkmcnt(0)
	v_add_f32_e32 v129, v129, v139
	ds_bpermute_b32 v139, v108, v129
	s_waitcnt lgkmcnt(0)
	v_add_f32_e32 v129, v129, v139
	ds_bpermute_b32 v139, v109, v129
	s_waitcnt lgkmcnt(0)
	v_add_f32_e32 v129, v129, v139
	ds_bpermute_b32 v139, v110, v129
	s_waitcnt lgkmcnt(0)
	v_add_f32_e32 v129, v129, v139
	ds_bpermute_b32 v139, v111, v129
	s_waitcnt lgkmcnt(0)
	v_add_f32_e32 v129, v129, v139
	ds_bpermute_b32 v139, v112, v129
	s_waitcnt lgkmcnt(0)
	v_add_f32_e32 v129, v129, v139
	v_fma_f32 v129, v129, s16, v102
	v_rsq_f32_e32 v129, v129
	s_nop 0
	s_waitcnt vmcnt(28)
	v_pk_add_f32 v[228:229], v[228:229], 1.0 op_sel_hi:[1,0]
	v_pk_add_f32 v[230:231], v[230:231], 1.0 op_sel_hi:[1,0]
	v_pk_add_f32 v[232:233], v[232:233], 1.0 op_sel_hi:[1,0]
	v_pk_add_f32 v[234:235], v[234:235], 1.0 op_sel_hi:[1,0]
	v_pk_add_f32 v[236:237], v[236:237], 1.0 op_sel_hi:[1,0]
	v_pk_add_f32 v[238:239], v[238:239], 1.0 op_sel_hi:[1,0]
	v_pk_add_f32 v[240:241], v[240:241], 1.0 op_sel_hi:[1,0]
	v_pk_add_f32 v[242:243], v[242:243], 1.0 op_sel_hi:[1,0]
	v_mul_f32_e32 v48, v48, v129
	v_mul_f32_e32 v49, v49, v129
	v_mul_f32_e32 v50, v50, v129
	v_mul_f32_e32 v51, v51, v129
	v_pk_mul_f32 v[48:49], v[48:49], v[144:145]
	v_pk_mul_f32 v[50:51], v[50:51], v[146:147]
	v_pk_fma_f32 v[48:49], v[48:49], v[228:229], v[244:245]
	v_pk_fma_f32 v[50:51], v[50:51], v[230:231], v[246:247]
	v_cvt_pk_bf16_f32 v48, v48, v49
	v_cvt_pk_bf16_f32 v49, v50, v51
	global_store_dwordx2 v96, v[48:49], s[46:47]
	v_mul_f32_e32 v52, v52, v129
	v_mul_f32_e32 v53, v53, v129
	v_mul_f32_e32 v54, v54, v129
	v_mul_f32_e32 v55, v55, v129
	v_pk_mul_f32 v[52:53], v[52:53], v[148:149]
	v_pk_mul_f32 v[54:55], v[54:55], v[150:151]
	v_pk_fma_f32 v[52:53], v[52:53], v[232:233], v[248:249]
	v_pk_fma_f32 v[54:55], v[54:55], v[234:235], v[250:251]
	v_cvt_pk_bf16_f32 v52, v52, v53
	v_cvt_pk_bf16_f32 v53, v54, v55
	global_store_dwordx2 v96, v[52:53], s[46:47] offset:512
	v_mul_f32_e32 v56, v56, v129
	v_mul_f32_e32 v57, v57, v129
	v_mul_f32_e32 v58, v58, v129
	v_mul_f32_e32 v59, v59, v129
	v_pk_mul_f32 v[56:57], v[56:57], v[152:153]
	v_pk_mul_f32 v[58:59], v[58:59], v[154:155]
	v_pk_fma_f32 v[56:57], v[56:57], v[236:237], v[118:119]
	v_pk_fma_f32 v[58:59], v[58:59], v[238:239], v[120:121]
	v_cvt_pk_bf16_f32 v56, v56, v57
	v_cvt_pk_bf16_f32 v57, v58, v59
	global_store_dwordx2 v96, v[56:57], s[46:47] offset:1024
	v_mul_f32_e32 v60, v60, v129
	v_mul_f32_e32 v61, v61, v129
	v_mul_f32_e32 v62, v62, v129
	v_mul_f32_e32 v63, v63, v129
	v_pk_mul_f32 v[60:61], v[60:61], v[156:157]
	v_pk_mul_f32 v[62:63], v[62:63], v[158:159]
	v_pk_fma_f32 v[60:61], v[60:61], v[240:241], v[122:123]
	v_pk_fma_f32 v[62:63], v[62:63], v[242:243], v[124:125]
	v_cvt_pk_bf16_f32 v60, v60, v61
	v_cvt_pk_bf16_f32 v61, v62, v63
	global_store_dwordx2 v96, v[60:61], s[46:47] offset:1536
	s_add_u32 s46, s46, 0x400000
	s_addc_u32 s47, s47, 0
	s_waitcnt vmcnt(63)
	v_mul_f32_e32 v132, v65, v65
	v_fmac_f32_e32 v132, v64, v64
	v_fmac_f32_e32 v132, v66, v66
	v_fmac_f32_e32 v132, v67, v67
	s_waitcnt vmcnt(62)
	v_mul_f32_e32 v133, v69, v69
	v_fmac_f32_e32 v133, v68, v68
	v_fmac_f32_e32 v133, v70, v70
	v_fmac_f32_e32 v133, v71, v71
	s_waitcnt vmcnt(61)
	v_mul_f32_e32 v134, v73, v73
	v_fmac_f32_e32 v134, v72, v72
	v_fmac_f32_e32 v134, v74, v74
	v_fmac_f32_e32 v134, v75, v75
	s_waitcnt vmcnt(60)
	v_mul_f32_e32 v135, v77, v77
	v_fmac_f32_e32 v135, v76, v76
	v_fmac_f32_e32 v135, v78, v78
	v_fmac_f32_e32 v135, v79, v79
	v_add_f32_e32 v130, v132, v133
	v_add_f32_e32 v130, v130, v134
	v_add_f32_e32 v130, v130, v135
	ds_bpermute_b32 v140, v103, v130
	s_waitcnt lgkmcnt(0)
	v_add_f32_e32 v130, v130, v140
	ds_bpermute_b32 v140, v108, v130
	s_waitcnt lgkmcnt(0)
	v_add_f32_e32 v130, v130, v140
	ds_bpermute_b32 v140, v109, v130
	s_waitcnt lgkmcnt(0)
	v_add_f32_e32 v130, v130, v140
	ds_bpermute_b32 v140, v110, v130
	s_waitcnt lgkmcnt(0)
	v_add_f32_e32 v130, v130, v140
	ds_bpermute_b32 v140, v111, v130
	s_waitcnt lgkmcnt(0)
	v_add_f32_e32 v130, v130, v140
	ds_bpermute_b32 v140, v112, v130
	s_waitcnt lgkmcnt(0)
	v_add_f32_e32 v130, v130, v140
	v_fma_f32 v130, v130, s16, v102
	v_rsq_f32_e32 v130, v130
	s_nop 0
	s_waitcnt vmcnt(16)
	v_pk_add_f32 v[160:161], v[160:161], 1.0 op_sel_hi:[1,0]
	v_pk_add_f32 v[162:163], v[162:163], 1.0 op_sel_hi:[1,0]
	v_pk_add_f32 v[164:165], v[164:165], 1.0 op_sel_hi:[1,0]
	v_pk_add_f32 v[166:167], v[166:167], 1.0 op_sel_hi:[1,0]
	v_pk_add_f32 v[168:169], v[168:169], 1.0 op_sel_hi:[1,0]
	v_pk_add_f32 v[170:171], v[170:171], 1.0 op_sel_hi:[1,0]
	v_pk_add_f32 v[172:173], v[172:173], 1.0 op_sel_hi:[1,0]
	v_pk_add_f32 v[174:175], v[174:175], 1.0 op_sel_hi:[1,0]
	v_mul_f32_e32 v64, v64, v130
	v_mul_f32_e32 v65, v65, v130
	v_mul_f32_e32 v66, v66, v130
	v_mul_f32_e32 v67, v67, v130
	v_pk_mul_f32 v[64:65], v[64:65], v[144:145]
	v_pk_mul_f32 v[66:67], v[66:67], v[146:147]
	v_pk_fma_f32 v[64:65], v[64:65], v[160:161], v[176:177]
	v_pk_fma_f32 v[66:67], v[66:67], v[162:163], v[178:179]
	v_cvt_pk_bf16_f32 v64, v64, v65
	v_cvt_pk_bf16_f32 v65, v66, v67
	global_store_dwordx2 v96, v[64:65], s[46:47]
	v_mul_f32_e32 v68, v68, v130
	v_mul_f32_e32 v69, v69, v130
	v_mul_f32_e32 v70, v70, v130
	v_mul_f32_e32 v71, v71, v130
	v_pk_mul_f32 v[68:69], v[68:69], v[148:149]
	v_pk_mul_f32 v[70:71], v[70:71], v[150:151]
	v_pk_fma_f32 v[68:69], v[68:69], v[164:165], v[180:181]
	v_pk_fma_f32 v[70:71], v[70:71], v[166:167], v[182:183]
	v_cvt_pk_bf16_f32 v68, v68, v69
	v_cvt_pk_bf16_f32 v69, v70, v71
	global_store_dwordx2 v96, v[68:69], s[46:47] offset:512
	v_mul_f32_e32 v72, v72, v130
	v_mul_f32_e32 v73, v73, v130
	v_mul_f32_e32 v74, v74, v130
	v_mul_f32_e32 v75, v75, v130
	v_pk_mul_f32 v[72:73], v[72:73], v[152:153]
	v_pk_mul_f32 v[74:75], v[74:75], v[154:155]
	v_pk_fma_f32 v[72:73], v[72:73], v[168:169], v[184:185]
	v_pk_fma_f32 v[74:75], v[74:75], v[170:171], v[186:187]
	v_cvt_pk_bf16_f32 v72, v72, v73
	v_cvt_pk_bf16_f32 v73, v74, v75
	global_store_dwordx2 v96, v[72:73], s[46:47] offset:1024
	v_mul_f32_e32 v76, v76, v130
	v_mul_f32_e32 v77, v77, v130
	v_mul_f32_e32 v78, v78, v130
	v_mul_f32_e32 v79, v79, v130
	v_pk_mul_f32 v[76:77], v[76:77], v[156:157]
	v_pk_mul_f32 v[78:79], v[78:79], v[158:159]
	v_pk_fma_f32 v[76:77], v[76:77], v[172:173], v[188:189]
	v_pk_fma_f32 v[78:79], v[78:79], v[174:175], v[190:191]
	v_cvt_pk_bf16_f32 v76, v76, v77
	v_cvt_pk_bf16_f32 v77, v78, v79
	global_store_dwordx2 v96, v[76:77], s[46:47] offset:1536
	s_add_u32 s46, s46, 0x400000
	s_addc_u32 s47, s47, 0
	s_waitcnt vmcnt(63)
	v_mul_f32_e32 v132, v81, v81
	v_fmac_f32_e32 v132, v80, v80
	v_fmac_f32_e32 v132, v82, v82
	v_fmac_f32_e32 v132, v83, v83
	s_waitcnt vmcnt(62)
	v_mul_f32_e32 v133, v85, v85
	v_fmac_f32_e32 v133, v84, v84
	v_fmac_f32_e32 v133, v86, v86
	v_fmac_f32_e32 v133, v87, v87
	s_waitcnt vmcnt(61)
	v_mul_f32_e32 v134, v89, v89
	v_fmac_f32_e32 v134, v88, v88
	v_fmac_f32_e32 v134, v90, v90
	v_fmac_f32_e32 v134, v91, v91
	s_waitcnt vmcnt(60)
	v_mul_f32_e32 v135, v93, v93
	v_fmac_f32_e32 v135, v92, v92
	v_fmac_f32_e32 v135, v94, v94
	v_fmac_f32_e32 v135, v95, v95
	v_add_f32_e32 v131, v132, v133
	v_add_f32_e32 v131, v131, v134
	v_add_f32_e32 v131, v131, v135
	ds_bpermute_b32 v141, v103, v131
	s_waitcnt lgkmcnt(0)
	v_add_f32_e32 v131, v131, v141
	ds_bpermute_b32 v141, v108, v131
	s_waitcnt lgkmcnt(0)
	v_add_f32_e32 v131, v131, v141
	ds_bpermute_b32 v141, v109, v131
	s_waitcnt lgkmcnt(0)
	v_add_f32_e32 v131, v131, v141
	ds_bpermute_b32 v141, v110, v131
	s_waitcnt lgkmcnt(0)
	v_add_f32_e32 v131, v131, v141
	ds_bpermute_b32 v141, v111, v131
	s_waitcnt lgkmcnt(0)
	v_add_f32_e32 v131, v131, v141
	ds_bpermute_b32 v141, v112, v131
	s_waitcnt lgkmcnt(0)
	v_add_f32_e32 v131, v131, v141
	v_fma_f32 v131, v131, s16, v102
	v_rsq_f32_e32 v131, v131
	s_nop 0
	s_waitcnt vmcnt(8)
	v_pk_add_f32 v[196:197], v[196:197], 1.0 op_sel_hi:[1,0]
	v_pk_add_f32 v[198:199], v[198:199], 1.0 op_sel_hi:[1,0]
	v_pk_add_f32 v[200:201], v[200:201], 1.0 op_sel_hi:[1,0]
	v_pk_add_f32 v[202:203], v[202:203], 1.0 op_sel_hi:[1,0]
	v_pk_add_f32 v[204:205], v[204:205], 1.0 op_sel_hi:[1,0]
	v_pk_add_f32 v[206:207], v[206:207], 1.0 op_sel_hi:[1,0]
	v_pk_add_f32 v[208:209], v[208:209], 1.0 op_sel_hi:[1,0]
	v_pk_add_f32 v[210:211], v[210:211], 1.0 op_sel_hi:[1,0]
	v_mul_f32_e32 v80, v80, v131
	v_mul_f32_e32 v81, v81, v131
	v_mul_f32_e32 v82, v82, v131
	v_mul_f32_e32 v83, v83, v131
	v_pk_mul_f32 v[80:81], v[80:81], v[144:145]
	v_pk_mul_f32 v[82:83], v[82:83], v[146:147]
	v_pk_fma_f32 v[80:81], v[80:81], v[196:197], v[212:213]
	v_pk_fma_f32 v[82:83], v[82:83], v[198:199], v[214:215]
	v_cvt_pk_bf16_f32 v80, v80, v81
	v_cvt_pk_bf16_f32 v81, v82, v83
	global_store_dwordx2 v96, v[80:81], s[46:47]
	v_mul_f32_e32 v84, v84, v131
	v_mul_f32_e32 v85, v85, v131
	v_mul_f32_e32 v86, v86, v131
	v_mul_f32_e32 v87, v87, v131
	v_pk_mul_f32 v[84:85], v[84:85], v[148:149]
	v_pk_mul_f32 v[86:87], v[86:87], v[150:151]
	v_pk_fma_f32 v[84:85], v[84:85], v[200:201], v[216:217]
	v_pk_fma_f32 v[86:87], v[86:87], v[202:203], v[218:219]
	v_cvt_pk_bf16_f32 v84, v84, v85
	v_cvt_pk_bf16_f32 v85, v86, v87
	global_store_dwordx2 v96, v[84:85], s[46:47] offset:512
	v_mul_f32_e32 v88, v88, v131
	v_mul_f32_e32 v89, v89, v131
	v_mul_f32_e32 v90, v90, v131
	v_mul_f32_e32 v91, v91, v131
	v_pk_mul_f32 v[88:89], v[88:89], v[152:153]
	v_pk_mul_f32 v[90:91], v[90:91], v[154:155]
	v_pk_fma_f32 v[88:89], v[88:89], v[204:205], v[220:221]
	v_pk_fma_f32 v[90:91], v[90:91], v[206:207], v[222:223]
	v_cvt_pk_bf16_f32 v88, v88, v89
	v_cvt_pk_bf16_f32 v89, v90, v91
	global_store_dwordx2 v96, v[88:89], s[46:47] offset:1024
	v_mul_f32_e32 v92, v92, v131
	v_mul_f32_e32 v93, v93, v131
	v_mul_f32_e32 v94, v94, v131
	v_mul_f32_e32 v95, v95, v131
	v_pk_mul_f32 v[92:93], v[92:93], v[156:157]
	v_pk_mul_f32 v[94:95], v[94:95], v[158:159]
	v_pk_fma_f32 v[92:93], v[92:93], v[208:209], v[224:225]
	v_pk_fma_f32 v[94:95], v[94:95], v[210:211], v[226:227]
	v_cvt_pk_bf16_f32 v92, v92, v93
	v_cvt_pk_bf16_f32 v93, v94, v95
	global_store_dwordx2 v96, v[92:93], s[46:47] offset:1536
